# plus: top-k scalar tails made independent per query (no shared temporaries)
# baseline (speedup 1.0000x reference)
.Ltk_bit_loop:
	s_or_b32 s14, s14, s32
	s_or_b32 s15, s15, s32
	s_or_b32 s16, s16, s32
	s_or_b32 s17, s17, s32
	v_cmp_le_u32_e64 s[22:23], s14, v0
	v_cmp_le_u32_e64 s[24:25], s14, v8
	v_cmp_le_u32_e64 s[26:27], s15, v1
	v_cmp_le_u32_e64 s[28:29], s15, v9
	v_cmp_le_u32_e64 s[30:31], s16, v2
	v_cmp_le_u32_e64 vcc, s16, v10
	v_cmp_le_u32_e64 s[34:35], s17, v3
	v_cmp_le_u32_e64 s[38:39], s17, v11
	s_or_b32 s18, s18, s32
	s_or_b32 s19, s19, s32
	s_or_b32 s20, s20, s32
	s_or_b32 s21, s21, s32
	v_cmp_le_u32_e64 s[40:41], s18, v4
	v_cmp_le_u32_e64 s[42:43], s18, v12
	v_cmp_le_u32_e64 s[44:45], s19, v5
	v_cmp_le_u32_e64 s[46:47], s19, v13
	v_cmp_le_u32_e64 s[0:1], s20, v6
	v_cmp_le_u32_e64 s[2:3], s20, v14
	v_cmp_le_u32_e64 s[4:5], s21, v7
	v_cmp_le_u32_e64 s[10:11], s21, v15
	s_bcnt1_i32_b64 s22, s[22:23]
	s_bcnt1_i32_b64 s26, s[26:27]
	s_bcnt1_i32_b64 s30, s[30:31]
	s_bcnt1_i32_b64 s34, s[34:35]
	s_bcnt1_i32_b64 s24, s[24:25]
	s_bcnt1_i32_b64 s28, s[28:29]
	s_bcnt1_i32_b64 vcc_lo, vcc
	s_bcnt1_i32_b64 s38, s[38:39]
	s_add_i32 s22, s22, s24
	s_add_i32 s26, s26, s28
	s_add_i32 s30, s30, vcc_lo
	s_add_i32 s34, s34, s38
	s_cmp_gt_u32 s22, 14
	s_cselect_b32 s22, 0, s32
	s_cmp_gt_u32 s26, 14
	s_cselect_b32 s26, 0, s32
	s_cmp_gt_u32 s30, 14
	s_cselect_b32 s30, 0, s32
	s_cmp_gt_u32 s34, 14
	s_cselect_b32 s34, 0, s32
	s_xor_b32 s14, s14, s22
	s_xor_b32 s15, s15, s26
	s_xor_b32 s16, s16, s30
	s_xor_b32 s17, s17, s34
	s_bcnt1_i32_b64 s40, s[40:41]
	s_bcnt1_i32_b64 s44, s[44:45]
	s_bcnt1_i32_b64 s0, s[0:1]
	s_bcnt1_i32_b64 s4, s[4:5]
	s_bcnt1_i32_b64 s42, s[42:43]
	s_bcnt1_i32_b64 s46, s[46:47]
	s_bcnt1_i32_b64 s2, s[2:3]
	s_bcnt1_i32_b64 s10, s[10:11]
	s_add_i32 s40, s40, s42
	s_add_i32 s44, s44, s46
	s_add_i32 s0, s0, s2
	s_add_i32 s4, s4, s10
	s_cmp_gt_u32 s40, 14
	s_cselect_b32 s40, 0, s32
	s_cmp_gt_u32 s44, 14
	s_cselect_b32 s44, 0, s32
	s_cmp_gt_u32 s0, 14
	s_cselect_b32 s0, 0, s32
	s_cmp_gt_u32 s4, 14
	s_cselect_b32 s4, 0, s32
	s_xor_b32 s18, s18, s40
	s_xor_b32 s19, s19, s44
	s_xor_b32 s20, s20, s0
	s_xor_b32 s21, s21, s4
	s_and_b32 s48, s32, 0x11110
	s_cbranch_scc0 .Ltk_nocheck
	v_cmp_le_u32_e64 s[22:23], s14, v0
	v_cmp_le_u32_e64 s[24:25], s14, v8
	v_cmp_le_u32_e64 s[26:27], s15, v1
	v_cmp_le_u32_e64 s[28:29], s15, v9
	v_cmp_le_u32_e64 s[30:31], s16, v2
	v_cmp_le_u32_e64 vcc, s16, v10
	v_cmp_le_u32_e64 s[34:35], s17, v3
	v_cmp_le_u32_e64 s[38:39], s17, v11
	v_cmp_le_u32_e64 s[40:41], s18, v4
	v_cmp_le_u32_e64 s[42:43], s18, v12
	v_cmp_le_u32_e64 s[44:45], s19, v5
	v_cmp_le_u32_e64 s[46:47], s19, v13
	v_cmp_le_u32_e64 s[0:1], s20, v6
	v_cmp_le_u32_e64 s[2:3], s20, v14
	v_cmp_le_u32_e64 s[4:5], s21, v7
	v_cmp_le_u32_e64 s[10:11], s21, v15
	s_mov_b32 s49, 0
	s_bcnt1_i32_b64 s48, s[22:23]
	s_bcnt1_i32_b64 s22, s[24:25]
	s_add_i32 s48, s48, s22
	s_xor_b32 s48, s48, 15
	s_or_b32 s49, s49, s48
	s_bcnt1_i32_b64 s48, s[26:27]
	s_bcnt1_i32_b64 s26, s[28:29]
	s_add_i32 s48, s48, s26
	s_xor_b32 s48, s48, 15
	s_or_b32 s49, s49, s48
	s_bcnt1_i32_b64 s48, s[30:31]
	s_bcnt1_i32_b64 s30, vcc
	s_add_i32 s48, s48, s30
	s_xor_b32 s48, s48, 15
	s_or_b32 s49, s49, s48
	s_bcnt1_i32_b64 s48, s[34:35]
	s_bcnt1_i32_b64 s34, s[38:39]
	s_add_i32 s48, s48, s34
	s_xor_b32 s48, s48, 15
	s_or_b32 s49, s49, s48
	s_bcnt1_i32_b64 s48, s[40:41]
	s_bcnt1_i32_b64 s40, s[42:43]
	s_add_i32 s48, s48, s40
	s_xor_b32 s48, s48, 15
	s_or_b32 s49, s49, s48
	s_bcnt1_i32_b64 s48, s[44:45]
	s_bcnt1_i32_b64 s44, s[46:47]
	s_add_i32 s48, s48, s44
	s_xor_b32 s48, s48, 15
	s_or_b32 s49, s49, s48
	s_bcnt1_i32_b64 s48, s[0:1]
	s_bcnt1_i32_b64 s0, s[2:3]
	s_add_i32 s48, s48, s0
	s_xor_b32 s48, s48, 15
	s_or_b32 s49, s49, s48
	s_bcnt1_i32_b64 s48, s[4:5]
	s_bcnt1_i32_b64 s4, s[10:11]
	s_add_i32 s48, s48, s4
	s_xor_b32 s48, s48, 15
	s_or_b32 s49, s49, s48
	s_cmp_eq_u32 s49, 0
	s_cbranch_scc1 .Ltk_done
